# phase 11 F128 side task: item loop rewritten by hand (lanes own items, waves split t, bank-skewed cosine table, partial sums combined through LDS)
# baseline (speedup 1.0000x reference)
.LBB0_1186:
	v_or_b32_e32 v1, 0x200, v128
	v_cvt_f32_u32_e32 v0, v128
	v_cvt_f32_u32_e32 v1, v1
	s_mov_b32 s4, 0x3a800000
	v_mov_b32_e32 v10, 0xbf1f24be
	v_mov_b32_e32 v12, 0x3e642e9d
	v_pk_mul_f32 v[0:1], v[0:1], s[4:5] op_sel_hi:[1,0]
	s_mov_b32 s5, 0x7f800000
	s_waitcnt lgkmcnt(0)
	v_pk_mul_f32 v[2:3], v[0:1], 0.5 op_sel_hi:[1,0]
	s_brev_b32 s6, 1
	v_fract_f32_e32 v4, v2
	v_fract_f32_e32 v5, v3
	v_pk_add_f32 v[4:5], v[4:5], v[4:5]
	v_cmp_neq_f32_e32 vcc, s5, v2
	v_mov_b32_e32 v11, 0x40234736
	v_mov_b32_e32 v14, 0xc0a55e0e
	v_cndmask_b32_e32 v2, 0, v4, vcc
	v_cmp_neq_f32_e32 vcc, s5, v3
	v_mov_b32_e32 v16, 0xbfaad1da
	v_mov_b32_e32 v17, 0xc09de9e6
	v_cndmask_b32_e32 v3, 0, v5, vcc
	v_cmp_lt_f32_e32 vcc, 1.0, v1
	s_ashr_i32 s23, s61, 11
	s_nop 0
	v_cndmask_b32_e32 v3, v1, v3, vcc
	v_cmp_lt_f32_e32 vcc, 1.0, v0
	s_nop 1
	v_cndmask_b32_e32 v2, v0, v2, vcc
	v_pk_add_f32 v[4:5], v[2:3], v[2:3]
	s_nop 0
	v_rndne_f32_e32 v5, v5
	v_rndne_f32_e32 v4, v4
	v_pk_fma_f32 v[2:3], v[4:5], -0.5, v[2:3] op_sel_hi:[1,0,1]
	v_cvt_i32_f32_e32 v8, v5
	v_cvt_i32_f32_e32 v9, v4
	v_pk_mul_f32 v[4:5], v[2:3], v[2:3]
	s_nop 0
	v_fmamk_f32 v6, v4, 0x3e75aa41, v10
	v_fmaak_f32 v6, v4, v6, 0x40234736
	v_fmamk_f32 v13, v4, 0x3d4be544, v12
	v_fmaak_f32 v15, v4, v6, 0xc0a55e0e
	v_pk_mul_f32 v[6:7], v[2:3], v[4:5]
	v_fmaak_f32 v13, v4, v13, 0xbfaad1da
	v_mul_f32_e32 v6, v6, v15
	v_fmaak_f32 v13, v4, v13, 0x4081e0d3
	v_fmac_f32_e32 v6, 0x40490fdb, v2
	v_fmaak_f32 v2, v4, v13, 0xc09de9e6
	v_and_b32_e32 v13, 1, v9
	v_fma_f32 v2, v4, v2, 1.0
	v_cmp_eq_u32_e32 vcc, 0, v13
	v_lshlrev_b32_e32 v4, 30, v9
	v_mov_b32_e32 v13, 0x7fc00000
	v_cndmask_b32_e64 v2, -v6, v2, vcc
	v_bitop3_b32 v2, v4, v2, s6 bitop3:0x6c
	v_cmp_lg_f32_e32 vcc, s5, v0
	v_fmamk_f32 v6, v5, 0x3d4be544, v12
	v_fmaak_f32 v6, v5, v6, 0xbfaad1da
	v_cndmask_b32_e32 v0, v13, v2, vcc
	v_fmamk_f32 v2, v5, 0x3e75aa41, v10
	v_fmaak_f32 v2, v5, v2, 0x40234736
	v_fmaak_f32 v2, v5, v2, 0xc0a55e0e
	v_mul_f32_e32 v2, v7, v2
	v_fmaak_f32 v6, v5, v6, 0x4081e0d3
	v_fmac_f32_e32 v2, 0x40490fdb, v3
	v_fmaak_f32 v3, v5, v6, 0xc09de9e6
	v_and_b32_e32 v6, 1, v8
	v_fma_f32 v3, v5, v3, 1.0
	v_cmp_eq_u32_e32 vcc, 0, v6
	v_or_b32_e32 v6, 0x400, v128
	v_lshl_add_u32 v4, v128, 2, 0
	v_cndmask_b32_e64 v2, -v2, v3, vcc
	v_lshlrev_b32_e32 v3, 30, v8
	v_bitop3_b32 v5, v3, v2, s6 bitop3:0x6c
	v_or_b32_e32 v2, 0x600, v128
	v_cvt_f32_u32_e32 v3, v2
	v_cvt_f32_u32_e32 v2, v6
	v_cmp_lg_f32_e32 vcc, s5, v1
	v_mov_b32_e32 v15, 0x4081e0d3
	s_nop 0
	v_cndmask_b32_e32 v1, v13, v5, vcc
	ds_write2st64_b32 v4, v0, v1 offset1:8
	v_pk_mul_f32 v[0:1], v[2:3], s[4:5] op_sel_hi:[1,0]
	s_add_i32 s4, s61, 0xbf
	v_pk_mul_f32 v[2:3], v[0:1], 0.5 op_sel_hi:[1,0]
	s_ashr_i32 s20, s4, 11
	v_fract_f32_e32 v6, v2
	v_fract_f32_e32 v7, v3
	v_pk_add_f32 v[6:7], v[6:7], v[6:7]
	v_cmp_neq_f32_e32 vcc, s5, v2
	s_cmp_gt_i32 s23, s20
	s_nop 0
	v_cndmask_b32_e32 v2, 0, v6, vcc
	v_cmp_neq_f32_e32 vcc, s5, v3
	s_nop 1
	v_cndmask_b32_e32 v3, 0, v7, vcc
	v_cmp_lt_f32_e32 vcc, 1.0, v1
	s_nop 1
	v_cndmask_b32_e32 v3, v1, v3, vcc
	v_cmp_lt_f32_e32 vcc, 1.0, v0
	s_nop 1
	v_cndmask_b32_e32 v2, v0, v2, vcc
	v_pk_add_f32 v[6:7], v[2:3], v[2:3]
	s_nop 0
	v_rndne_f32_e32 v7, v7
	v_rndne_f32_e32 v6, v6
	v_pk_fma_f32 v[2:3], v[6:7], -0.5, v[2:3] op_sel_hi:[1,0,1]
	v_cvt_i32_f32_e32 v5, v7
	v_cvt_i32_f32_e32 v18, v6
	v_pk_mul_f32 v[6:7], v[2:3], v[2:3]
	s_nop 0
	v_fmamk_f32 v8, v6, 0x3e75aa41, v10
	v_fmaak_f32 v8, v6, v8, 0x40234736
	v_fmamk_f32 v19, v6, 0x3d4be544, v12
	v_fmaak_f32 v20, v6, v8, 0xc0a55e0e
	v_pk_mul_f32 v[8:9], v[2:3], v[6:7]
	v_fmaak_f32 v19, v6, v19, 0xbfaad1da
	v_mul_f32_e32 v8, v8, v20
	v_fmaak_f32 v19, v6, v19, 0x4081e0d3
	v_fmac_f32_e32 v8, 0x40490fdb, v2
	v_fmaak_f32 v2, v6, v19, 0xc09de9e6
	v_and_b32_e32 v19, 1, v18
	v_fma_f32 v2, v6, v2, 1.0
	v_cmp_eq_u32_e32 vcc, 0, v19
	v_fmac_f32_e32 v10, 0x3e75aa41, v7
	v_lshlrev_b32_e32 v6, 30, v18
	v_cndmask_b32_e64 v2, -v8, v2, vcc
	v_fmac_f32_e32 v11, v7, v10
	v_fmac_f32_e32 v12, 0x3d4be544, v7
	v_bitop3_b32 v2, v6, v2, s6 bitop3:0x6c
	v_cmp_lg_f32_e32 vcc, s5, v0
	v_fmac_f32_e32 v14, v7, v11
	v_fmac_f32_e32 v16, v7, v12
	v_cndmask_b32_e32 v0, v13, v2, vcc
	v_mul_f32_e32 v2, v9, v14
	v_fmac_f32_e32 v15, v7, v16
	v_fmac_f32_e32 v2, 0x40490fdb, v3
	v_fmac_f32_e32 v17, v7, v15
	v_and_b32_e32 v3, 1, v5
	v_fma_f32 v6, v7, v17, 1.0
	v_cmp_eq_u32_e32 vcc, 0, v3
	v_lshlrev_b32_e32 v3, 30, v5
	s_nop 0
	v_cndmask_b32_e64 v2, -v2, v6, vcc
	v_bitop3_b32 v2, v3, v2, s6 bitop3:0x6c
	v_cmp_lg_f32_e32 vcc, s5, v1
	s_nop 1
	v_cndmask_b32_e32 v1, v13, v2, vcc
	ds_write2st64_b32 v4, v0, v1 offset0:16 offset1:24
	s_cbranch_scc1 .LBB0_1196
	v_cmp_eq_u32_e64 s[4:5], 0, v131
	v_mov_b32_e32 v131, 0
	v_and_b32_e32 v8, 63, v128
	v_and_b32_e32 v0, 16, v128
	v_cmp_eq_u32_e64 s[8:9], 0, v129
	v_mov_b32_e32 v129, v131
	v_mul_u32_u24_e32 v5, 12, v128
	v_cmp_eq_u32_e64 s[6:7], 0, v0
	v_lshl_add_u64 v[0:1], s[12:13], 0, v[130:131]
	s_mov_b64 s[14:15], 0x1500000
	v_lshl_add_u64 v[2:3], v[128:129], 4, s[12:13]
	s_mov_b64 s[12:13], 0x1400000
	v_lshlrev_b32_e32 v11, 3, v8
	v_lshl_add_u32 v6, v8, 4, 0
	v_add_u32_e32 v24, v4, v5
	v_mbcnt_lo_u32_b32 v4, -1, 0
	s_add_i32 s21, s61, 0xc0
	v_lshl_add_u64 v[0:1], v[0:1], 0, s[14:15]
	v_lshl_add_u64 v[2:3], v[2:3], 0, s[12:13]
	v_or_b32_e32 v9, 0x1c0, v128
	v_or_b32_e32 v10, 0x180, v8
	s_lshl_b32 s22, s23, 11
	v_or_b32_e32 v12, 0xc00, v11
	v_or_b32_e32 v13, 0x140, v8
	v_or_b32_e32 v14, 0xa00, v11
	v_or_b32_e32 v15, 0x100, v8
	v_or_b32_e32 v16, 0x800, v11
	v_or_b32_e32 v17, 0xc0, v8
	v_or_b32_e32 v18, 0x600, v11
	v_or_b32_e32 v19, 0x80, v8
	v_or_b32_e32 v20, 0x400, v11
	v_or_b32_e32 v21, 64, v8
	v_or_b32_e32 v22, 0x200, v11
	v_add_u32_e32 v23, 0x2000, v6
	v_mbcnt_hi_u32_b32 v25, -1, v4
	s_waitcnt lgkmcnt(0)
	s_barrier
	v_add_u32_e32 v40, 0, v128
	v_lshlrev_b32_e32 v41, 2, v40
	ds_read_b32 v42, v41
	v_lshrrev_b32_e32 v43, 5, v40
	v_add_lshl_u32 v43, v40, v43, 2
	s_waitcnt lgkmcnt(0)
	ds_write_b32 v43, v42 offset:40960
	v_add_u32_e32 v40, 512, v128
	v_lshlrev_b32_e32 v41, 2, v40
	ds_read_b32 v42, v41
	v_lshrrev_b32_e32 v43, 5, v40
	v_add_lshl_u32 v43, v40, v43, 2
	s_waitcnt lgkmcnt(0)
	ds_write_b32 v43, v42 offset:40960
	v_add_u32_e32 v40, 1024, v128
	v_lshlrev_b32_e32 v41, 2, v40
	ds_read_b32 v42, v41
	v_lshrrev_b32_e32 v43, 5, v40
	v_add_lshl_u32 v43, v40, v43, 2
	s_waitcnt lgkmcnt(0)
	ds_write_b32 v43, v42 offset:40960
	v_add_u32_e32 v40, 1536, v128
	v_lshlrev_b32_e32 v41, 2, v40
	ds_read_b32 v42, v41
	v_lshrrev_b32_e32 v43, 5, v40
	v_add_lshl_u32 v43, v40, v43, 2
	s_waitcnt lgkmcnt(0)
	ds_write_b32 v43, v42 offset:40960
	s_branch .LBB0_1189

.LBB0_1189:
	s_mov_b32 s12, s23
	s_ashr_i32 s13, s23, 31
	s_lshl_b64 s[14:15], s[12:13], 15
	v_lshl_add_u64 v[30:31], v[2:3], 0, s[14:15]
	v_add_co_u32_e32 v32, vcc, 0x2000, v30
	s_waitcnt vmcnt(0) lgkmcnt(0)
	s_nop 0
	v_addc_co_u32_e32 v33, vcc, 0, v31, vcc
	v_add_co_u32_e32 v38, vcc, 0x4000, v30
	s_barrier
	s_nop 0
	v_addc_co_u32_e32 v39, vcc, 0, v31, vcc
	v_add_co_u32_e32 v40, vcc, 0x6000, v30
	global_load_dwordx4 v[4:7], v[30:31], off
	global_load_dwordx4 v[26:29], v[32:33], off
	v_addc_co_u32_e32 v41, vcc, 0, v31, vcc
	global_load_dwordx4 v[30:33], v[38:39], off
	global_load_dwordx4 v[34:37], v[40:41], off
	s_lshl_b32 s13, s23, 11
	s_add_i32 s23, s23, 1
	s_max_i32 s14, s61, s13
	s_lshl_b32 s13, s23, 11
	s_min_i32 s13, s21, s13
	s_cmp_ge_i32 s14, s13
	s_waitcnt vmcnt(3)
	ds_write_b128 v24, v[4:7] offset:8192
	s_waitcnt vmcnt(2)
	ds_write_b128 v24, v[26:29] offset:16384
	s_waitcnt vmcnt(1)
	ds_write_b128 v24, v[30:33] offset:24576
	s_waitcnt vmcnt(0)
	ds_write_b128 v24, v[34:37] offset:32768
	s_waitcnt lgkmcnt(0)
	s_barrier
	s_cbranch_scc1 .LBB0_1188
	s_sub_i32 s40, s13, s14
	s_lshr_b32 s40, s40, 6
	s_mov_b32 s41, 0
	s_lshl_b32 s43, s3, 8
	s_lshl_b32 s44, s3, 12
.Lf128_group:
	s_lshl_b32 s42, s41, 6
	s_add_i32 s42, s42, s14
	v_add_u32_e32 v40, s42, v25
	v_and_b32_e32 v41, 0x7ff, v40
	v_lshlrev_b32_e32 v42, 21, v41
	v_mul_lo_u32 v43, v41, s43
	v_lshlrev_b32_e32 v43, 21, v43
	v_mov_b32_e32 v44, 0
	v_mov_b32_e32 v45, 0
	v_mov_b32_e32 v46, 0
	v_mov_b32_e32 v47, 0
	v_mov_b32_e32 v48, s44
	s_mov_b32 s45, 0
.Lf128_t:
	ds_read_b128 v[52:55], v48 offset:8192
	ds_read_b128 v[56:59], v48 offset:8208
	ds_read_b128 v[60:63], v48 offset:8224
	ds_read_b128 v[64:67], v48 offset:8240
	v_lshrrev_b32_e32 v76, 21, v43
	v_lshrrev_b32_e32 v49, 26, v43
	v_add_lshl_u32 v76, v76, v49, 2
	ds_read_b32 v68, v76 offset:40960
	v_add_u32_e32 v43, v43, v42
	v_lshrrev_b32_e32 v77, 21, v43
	v_lshrrev_b32_e32 v49, 26, v43
	v_add_lshl_u32 v77, v77, v49, 2
	ds_read_b32 v70, v77 offset:40960
	v_add_u32_e32 v43, v43, v42
	v_lshrrev_b32_e32 v78, 21, v43
	v_lshrrev_b32_e32 v49, 26, v43
	v_add_lshl_u32 v78, v78, v49, 2
	ds_read_b32 v72, v78 offset:40960
	v_add_u32_e32 v43, v43, v42
	v_lshrrev_b32_e32 v79, 21, v43
	v_lshrrev_b32_e32 v49, 26, v43
	v_add_lshl_u32 v79, v79, v49, 2
	ds_read_b32 v74, v79 offset:40960
	v_add_u32_e32 v43, v43, v42
	s_waitcnt lgkmcnt(3)
	v_pk_fma_f32 v[44:45], v[52:53], v[68:69], v[44:45] op_sel_hi:[1,0,1]
	v_pk_fma_f32 v[46:47], v[54:55], v[68:69], v[46:47] op_sel_hi:[1,0,1]
	s_waitcnt lgkmcnt(2)
	v_pk_fma_f32 v[44:45], v[56:57], v[70:71], v[44:45] op_sel_hi:[1,0,1]
	v_pk_fma_f32 v[46:47], v[58:59], v[70:71], v[46:47] op_sel_hi:[1,0,1]
	s_waitcnt lgkmcnt(1)
	v_pk_fma_f32 v[44:45], v[60:61], v[72:73], v[44:45] op_sel_hi:[1,0,1]
	v_pk_fma_f32 v[46:47], v[62:63], v[72:73], v[46:47] op_sel_hi:[1,0,1]
	s_waitcnt lgkmcnt(0)
	v_pk_fma_f32 v[44:45], v[64:65], v[74:75], v[44:45] op_sel_hi:[1,0,1]
	v_pk_fma_f32 v[46:47], v[66:67], v[74:75], v[46:47] op_sel_hi:[1,0,1]
	v_add_u32_e32 v48, 64, v48
	s_add_i32 s45, s45, 4
	s_cmpk_lt_i32 s45, 0x100
	s_cbranch_scc1 .Lf128_t
	s_lshl_b32 s46, s41, 13
	s_lshl_b32 s47, s3, 10
	s_add_i32 s46, s46, s47
	v_lshl_add_u32 v50, v25, 4, s46
	ds_write_b128 v50, v[44:47] offset:50176
	s_add_i32 s41, s41, 1
	s_cmp_lt_u32 s41, s40
	s_cbranch_scc1 .Lf128_group
	s_waitcnt lgkmcnt(0)
	s_barrier
	s_lshl_b32 s45, s40, 6
	v_cmp_gt_u32_e32 vcc, s45, v128
	s_and_saveexec_b64 s[46:47], vcc
	v_lshrrev_b32_e32 v60, 6, v128
	v_lshlrev_b32_e32 v60, 13, v60
	v_and_b32_e32 v61, 63, v128
	v_lshl_add_u32 v60, v61, 4, v60
	ds_read_b128 v[64:67], v60 offset:50176
	ds_read_b128 v[68:71], v60 offset:51200
	ds_read_b128 v[72:75], v60 offset:52224
	ds_read_b128 v[76:79], v60 offset:53248
	ds_read_b128 v[80:83], v60 offset:54272
	ds_read_b128 v[84:87], v60 offset:55296
	ds_read_b128 v[88:91], v60 offset:56320
	ds_read_b128 v[92:95], v60 offset:57344
	s_add_u32 s48, s34, 0x1500000
	s_addc_u32 s49, s35, 0
	v_add_u32_e32 v62, s14, v128
	v_lshlrev_b32_e32 v62, 4, v62
	s_waitcnt lgkmcnt(0)
	v_pk_add_f32 v[64:65], v[64:65], v[68:69]
	v_pk_add_f32 v[66:67], v[66:67], v[70:71]
	v_pk_add_f32 v[64:65], v[64:65], v[72:73]
	v_pk_add_f32 v[66:67], v[66:67], v[74:75]
	v_pk_add_f32 v[64:65], v[64:65], v[76:77]
	v_pk_add_f32 v[66:67], v[66:67], v[78:79]
	v_pk_add_f32 v[64:65], v[64:65], v[80:81]
	v_pk_add_f32 v[66:67], v[66:67], v[82:83]
	v_pk_add_f32 v[64:65], v[64:65], v[84:85]
	v_pk_add_f32 v[66:67], v[66:67], v[86:87]
	v_pk_add_f32 v[64:65], v[64:65], v[88:89]
	v_pk_add_f32 v[66:67], v[66:67], v[90:91]
	v_pk_add_f32 v[64:65], v[64:65], v[92:93]
	v_pk_add_f32 v[66:67], v[66:67], v[94:95]
	v_mov_b32_e32 v63, 0x3cb504f3
	v_mul_f32_e32 v64, v63, v64
	v_mul_f32_e32 v65, v63, v65
	v_mul_f32_e32 v66, v63, v66
	v_mul_f32_e32 v67, v63, v67
	global_store_dwordx4 v62, v[64:67], s[48:49]
	s_mov_b64 exec, s[46:47]
	s_branch .LBB0_1188
